# Q-up / KV-up epilogues: bf16 store pairs widened to 16-byte stores via v_permlane16_swap; counted vmcnt waits tightened for the removed stores
# speedup vs baseline: 1.0562x; 1.0096x over previous
.LBB0_522:
	v_mbcnt_lo_u32_b32 v226, -1, 0
	v_mbcnt_hi_u32_b32 v226, -1, v226
	v_and_b32_e32 v226, 16, v226
	v_lshrrev_b32_e32 v227, 1, v226
	v_add_u32_e32 v226, v226, v227
	v_mov_b32_e32 v227, 0
	s_lshl_b32 s4, s66, 8
	v_mov_b32_e32 v106, v222
	v_mov_b32_e32 v157, v223
	s_add_i32 s4, s4, s41
	s_nop 0
	v_add_u32_e32 v186, s4, v106
	v_ashrrev_i32_e32 v187, 31, v186
	v_lshlrev_b64 v[184:185], 4, v[186:187]
	v_lshl_add_u64 v[106:107], s[90:91], 0, v[184:185]
	global_load_dwordx4 v[106:109], v[106:107], off
	v_add_u32_e32 v200, 16, v186
	v_ashrrev_i32_e32 v201, 31, v200
	v_lshlrev_b64 v[206:207], 4, v[200:201]
	s_mov_b32 s4, 0x3b800000
	v_add_u32_e32 v202, 32, v186
	v_add_u32_e32 v158, 0xb0, v186
	v_ashrrev_i32_e32 v203, 31, v202
	v_add_u32_e32 v196, 48, v186
	v_ashrrev_i32_e32 v159, 31, v158
	v_lshlrev_b64 v[204:205], 4, v[202:203]
	v_ashrrev_i32_e32 v197, 31, v196
	v_add_u32_e32 v190, 0x80, v186
	v_lshlrev_b64 v[160:161], 4, v[158:159]
	v_lshlrev_b64 v[198:199], 4, v[196:197]
	v_ashrrev_i32_e32 v191, 31, v190
	v_add_u32_e32 v182, 0x90, v186
	v_lshlrev_b64 v[194:195], 4, v[190:191]
	v_ashrrev_i32_e32 v183, 31, v182
	v_add_u32_e32 v178, 0xa0, v186
	v_lshlrev_b64 v[188:189], 4, v[182:183]
	v_ashrrev_i32_e32 v179, 31, v178
	v_lshlrev_b64 v[180:181], 4, v[178:179]
	v_lshlrev_b32_e32 v208, 2, v157
	v_ashrrev_i32_e32 v209, 31, v208
	v_lshlrev_b64 v[164:165], 2, v[208:209]
	v_lshl_add_u64 v[162:163], s[78:79], 0, v[164:165]
	v_lshl_add_u64 v[164:165], s[80:81], 0, v[164:165]
	s_waitcnt vmcnt(0)
	v_mov_b32_e32 v110, v107
	v_mov_b32_e32 v111, v108
	v_mov_b32_e32 v107, v109
	v_pk_add_f32 v[110:111], v[110:111], v[106:107]
	v_lshl_add_u64 v[106:107], s[90:91], 0, v[206:207]
	global_load_dwordx4 v[106:109], v[106:107], off
	s_waitcnt vmcnt(0)
	v_mov_b32_e32 v112, v107
	v_mov_b32_e32 v113, v108
	v_mov_b32_e32 v107, v109
	v_pk_add_f32 v[106:107], v[112:113], v[106:107]
	v_mov_b32_e32 v109, v110
	v_mov_b32_e32 v108, v106
	v_mov_b32_e32 v110, v107
	v_pk_add_f32 v[106:107], v[108:109], v[110:111]
	v_lshl_add_u64 v[110:111], s[90:91], 0, v[160:161]
	v_pk_fma_f32 v[192:193], v[106:107], s[4:5], v[166:167] op_sel_hi:[1,0,0]
	global_load_dwordx4 v[110:113], v[110:111], off
	v_mul_f32_e32 v106, 0x4b800000, v193
	v_cmp_gt_f32_e64 s[4:5], s29, v193
	v_cmp_gt_f32_e32 vcc, s29, v192
	s_nop 0
	v_cndmask_b32_e64 v106, v193, v106, s[4:5]
	v_rsq_f32_e32 v106, v106
	s_nop 0
	v_mul_f32_e32 v107, 0x45800000, v106
	v_cndmask_b32_e64 v106, v106, v107, s[4:5]
	v_mul_f32_e32 v156, 0x3e16c740, v106
	v_lshl_add_u64 v[106:107], s[90:91], 0, v[204:205]
	global_load_dwordx4 v[138:141], v[106:107], off
	v_lshl_add_u64 v[106:107], s[90:91], 0, v[198:199]
	global_load_dwordx4 v[142:145], v[106:107], off
	v_lshl_add_u64 v[106:107], s[90:91], 0, v[194:195]
	global_load_dwordx4 v[130:133], v[106:107], off
	v_lshl_add_u64 v[106:107], s[90:91], 0, v[188:189]
	global_load_dwordx4 v[134:137], v[106:107], off
	v_lshl_add_u64 v[106:107], s[90:91], 0, v[180:181]
	global_load_dwordx4 v[106:109], v[106:107], off
	s_lshl_b32 s4, s65, 8
	s_or_b32 s4, s4, s62
	s_ashr_i32 s15, s4, 5
	s_mul_hi_i32 s5, s15, 0x55555556
	s_lshr_b32 s6, s5, 31
	s_add_i32 s5, s5, s6
	s_mul_i32 s5, s5, 3
	s_sub_i32 s5, s15, s5
	s_cmp_eq_u32 s5, 2
	v_pk_mul_f32 v[210:211], v[152:153], v[156:157] op_sel_hi:[1,0]
	v_lshlrev_b64 v[152:153], 2, v[184:185]
	s_cselect_b64 s[58:59], -1, 0
	s_cmp_lg_u32 s5, 2
	v_pk_mul_f32 v[148:149], v[148:149], v[156:157] op_sel_hi:[1,0]
	v_pk_mul_f32 v[146:147], v[146:147], v[156:157] op_sel_hi:[1,0]
	v_pk_mul_f32 v[212:213], v[150:151], v[156:157] op_sel_hi:[1,0]
	v_lshl_add_u64 v[150:151], v[162:163], 0, v[152:153]
	v_lshl_add_u64 v[184:185], v[164:165], 0, v[152:153]
	s_cbranch_scc1 .LBB0_524
	global_load_dwordx4 v[168:171], v[184:185], off
	global_load_dwordx4 v[172:175], v[150:151], off
	s_waitcnt vmcnt(1)
	v_pk_mul_f32 v[152:153], v[210:211], v[170:171]
	v_pk_mul_f32 v[176:177], v[212:213], v[168:169]
	v_pk_mul_f32 v[170:171], v[148:149], v[170:171]
	v_pk_mul_f32 v[168:169], v[146:147], v[168:169]
	s_waitcnt vmcnt(0)
	v_pk_fma_f32 v[148:149], v[148:149], v[174:175], v[152:153] neg_lo:[0,0,1] neg_hi:[0,0,1]
	v_pk_fma_f32 v[146:147], v[146:147], v[172:173], v[176:177] neg_lo:[0,0,1] neg_hi:[0,0,1]
	v_pk_fma_f32 v[210:211], v[210:211], v[174:175], v[170:171]
	v_pk_fma_f32 v[212:213], v[212:213], v[172:173], v[168:169]
.LBB0_524:
	v_mul_f32_e32 v152, 0x4b800000, v192
	v_cndmask_b32_e32 v152, v192, v152, vcc
	v_rsq_f32_e32 v152, v152
	v_readlane_b32 s6, v253, 50
	v_readlane_b32 s7, v253, 51
	s_ashr_i32 s5, s4, 31
	v_mul_f32_e32 v153, 0x45800000, v152
	v_lshl_add_u64 v[168:169], v[208:209], 1, s[6:7]
	v_lshl_add_u64 v[192:193], s[4:5], 1, v[168:169]
	v_cndmask_b32_e32 v152, v152, v153, vcc
	v_mad_i64_i32 v[186:187], s[4:5], v186, s92, v[192:193]
	v_cvt_pk_bf16_f32 v228, v146, v147
	v_cvt_pk_bf16_f32 v229, v148, v149
	v_mul_f32_e32 v152, 0x3e16c740, v152
	v_cvt_pk_bf16_f32 v230, v212, v213
	v_cvt_pk_bf16_f32 v231, v210, v211
	s_nop 1
	v_permlane16_swap_b32_e32 v228, v230
	v_permlane16_swap_b32_e32 v229, v231
	v_lshl_add_u64 v[214:215], v[186:187], 0, v[226:227]
	global_store_dwordx4 v[214:215], v[228:231], off
	v_pk_mul_f32 v[146:147], v[124:125], v[152:153] op_sel_hi:[1,0]
	v_pk_mul_f32 v[148:149], v[122:123], v[152:153] op_sel_hi:[1,0]
	v_cndmask_b32_e64 v122, 0, 1, s[58:59]
	v_lshlrev_b64 v[124:125], 2, v[206:207]
	v_pk_mul_f32 v[128:129], v[128:129], v[152:153] op_sel_hi:[1,0]
	v_pk_mul_f32 v[126:127], v[126:127], v[152:153] op_sel_hi:[1,0]
	v_cmp_ne_u32_e64 s[6:7], 1, v122
	s_andn2_b64 vcc, exec, s[58:59]
	v_lshl_add_u64 v[122:123], v[162:163], 0, v[124:125]
	v_lshl_add_u64 v[124:125], v[164:165], 0, v[124:125]
	s_cbranch_vccnz .LBB0_526
	global_load_dwordx4 v[168:171], v[124:125], off
	global_load_dwordx4 v[172:175], v[122:123], off
	s_waitcnt vmcnt(0)
	v_pk_mul_f32 v[176:177], v[146:147], v[170:171]
	v_pk_mul_f32 v[206:207], v[148:149], v[168:169]
	v_pk_mul_f32 v[170:171], v[128:129], v[170:171]
	v_pk_mul_f32 v[168:169], v[126:127], v[168:169]
	s_waitcnt vmcnt(0)
	v_pk_fma_f32 v[128:129], v[128:129], v[174:175], v[176:177] neg_lo:[0,0,1] neg_hi:[0,0,1]
	v_pk_fma_f32 v[126:127], v[126:127], v[172:173], v[206:207] neg_lo:[0,0,1] neg_hi:[0,0,1]
	v_pk_fma_f32 v[146:147], v[146:147], v[174:175], v[170:171]
	v_pk_fma_f32 v[148:149], v[148:149], v[172:173], v[168:169]
.LBB0_526:
	s_waitcnt vmcnt(5)
	v_mov_b32_e32 v168, v139
	v_mov_b32_e32 v169, v140
	v_mov_b32_e32 v139, v141
	s_waitcnt vmcnt(4)
	v_mov_b32_e32 v140, v143
	v_mov_b32_e32 v141, v144
	v_mov_b32_e32 v143, v145
	v_pk_add_f32 v[138:139], v[168:169], v[138:139]
	v_pk_add_f32 v[140:141], v[140:141], v[142:143]
	v_mov_b32_e32 v143, v138
	v_mov_b32_e32 v142, v140
	v_mov_b32_e32 v138, v141
	v_pk_add_f32 v[138:139], v[142:143], v[138:139]
	s_mov_b32 s4, 0x3b800000
	v_pk_fma_f32 v[206:207], v[138:139], s[4:5], v[166:167] op_sel_hi:[1,0,0]
	v_mad_i64_i32 v[140:141], s[26:27], v200, s92, v[192:193]
	v_mul_f32_e32 v138, 0x4b800000, v207
	v_cmp_gt_f32_e32 vcc, s29, v207
	v_cvt_pk_bf16_f32 v232, v126, v127
	v_cvt_pk_bf16_f32 v233, v128, v129
	v_cndmask_b32_e32 v138, v207, v138, vcc
	v_rsq_f32_e32 v138, v138
	v_cvt_pk_bf16_f32 v234, v148, v149
	v_cvt_pk_bf16_f32 v235, v146, v147
	v_mul_f32_e32 v139, 0x45800000, v138
	v_cndmask_b32_e32 v138, v138, v139, vcc
	s_nop 1
	v_permlane16_swap_b32_e32 v232, v234
	v_permlane16_swap_b32_e32 v233, v235
	v_lshl_add_u64 v[216:217], v[140:141], 0, v[226:227]
	global_store_dwordx4 v[216:217], v[232:235], off
	v_mul_f32_e32 v138, 0x3e16c740, v138
	v_pk_mul_f32 v[144:145], v[114:115], v[138:139] op_sel_hi:[1,0]
	v_lshlrev_b64 v[114:115], 2, v[204:205]
	v_cmp_gt_f32_e64 s[4:5], s29, v206
	v_pk_mul_f32 v[120:121], v[120:121], v[138:139] op_sel_hi:[1,0]
	v_pk_mul_f32 v[118:119], v[118:119], v[138:139] op_sel_hi:[1,0]
	v_pk_mul_f32 v[142:143], v[116:117], v[138:139] op_sel_hi:[1,0]
	s_and_b64 vcc, exec, s[6:7]
	v_lshl_add_u64 v[116:117], v[162:163], 0, v[114:115]
	v_lshl_add_u64 v[126:127], v[164:165], 0, v[114:115]
	s_cbranch_vccnz .LBB0_528
	global_load_dwordx4 v[146:149], v[126:127], off
	global_load_dwordx4 v[168:171], v[116:117], off
	s_waitcnt vmcnt(0)
	v_pk_mul_f32 v[114:115], v[142:143], v[148:149]
	v_pk_mul_f32 v[128:129], v[144:145], v[146:147]
	v_pk_mul_f32 v[148:149], v[120:121], v[148:149]
	v_pk_mul_f32 v[146:147], v[118:119], v[146:147]
	s_waitcnt vmcnt(0)
	v_pk_fma_f32 v[120:121], v[120:121], v[170:171], v[114:115] neg_lo:[0,0,1] neg_hi:[0,0,1]
	v_pk_fma_f32 v[118:119], v[118:119], v[168:169], v[128:129] neg_lo:[0,0,1] neg_hi:[0,0,1]
	v_pk_fma_f32 v[142:143], v[142:143], v[170:171], v[148:149]
	v_pk_fma_f32 v[144:145], v[144:145], v[168:169], v[146:147]
.LBB0_528:
	v_mul_f32_e32 v114, 0x4b800000, v206
	v_cndmask_b32_e64 v114, v206, v114, s[4:5]
	v_rsq_f32_e32 v114, v114
	v_cvt_pk_bf16_f32 v236, v118, v119
	v_cvt_pk_bf16_f32 v237, v120, v121
	s_and_b64 vcc, exec, s[6:7]
	v_mul_f32_e32 v115, 0x45800000, v114
	v_cndmask_b32_e64 v114, v114, v115, s[4:5]
	v_mul_f32_e32 v114, 0x3e16c740, v114
	v_mad_i64_i32 v[128:129], s[4:5], v202, s92, v[192:193]
	v_cvt_pk_bf16_f32 v239, v142, v143
	v_pk_mul_f32 v[142:143], v[100:101], v[114:115] op_sel_hi:[1,0]
	v_lshlrev_b64 v[100:101], 2, v[198:199]
	v_cvt_pk_bf16_f32 v238, v144, v145
	v_pk_mul_f32 v[104:105], v[104:105], v[114:115] op_sel_hi:[1,0]
	v_pk_mul_f32 v[102:103], v[102:103], v[114:115] op_sel_hi:[1,0]
	v_pk_mul_f32 v[144:145], v[98:99], v[114:115] op_sel_hi:[1,0]
	v_lshl_add_u64 v[98:99], v[162:163], 0, v[100:101]
	v_lshl_add_u64 v[100:101], v[164:165], 0, v[100:101]
	s_nop 1
	v_permlane16_swap_b32_e32 v236, v238
	v_permlane16_swap_b32_e32 v237, v239
	v_lshl_add_u64 v[218:219], v[128:129], 0, v[226:227]
	global_store_dwordx4 v[218:219], v[236:239], off
	s_cbranch_vccnz .LBB0_530
	global_load_dwordx4 v[118:121], v[100:101], off
	global_load_dwordx4 v[146:149], v[98:99], off
	s_waitcnt vmcnt(0)
	v_pk_mul_f32 v[168:169], v[142:143], v[120:121]
	v_pk_mul_f32 v[170:171], v[144:145], v[118:119]
	v_pk_mul_f32 v[120:121], v[104:105], v[120:121]
	v_pk_mul_f32 v[118:119], v[102:103], v[118:119]
	s_waitcnt vmcnt(0)
	v_pk_fma_f32 v[104:105], v[104:105], v[148:149], v[168:169] neg_lo:[0,0,1] neg_hi:[0,0,1]
	v_pk_fma_f32 v[102:103], v[102:103], v[146:147], v[170:171] neg_lo:[0,0,1] neg_hi:[0,0,1]
	v_pk_fma_f32 v[142:143], v[142:143], v[148:149], v[120:121]
	v_pk_fma_f32 v[144:145], v[144:145], v[146:147], v[118:119]
.LBB0_530:
	s_waitcnt vmcnt(5)
	v_mov_b32_e32 v118, v131
	v_mov_b32_e32 v119, v132
	v_mov_b32_e32 v131, v133
	s_waitcnt vmcnt(4)
	v_mov_b32_e32 v120, v135
	v_mov_b32_e32 v121, v136
	v_mov_b32_e32 v135, v137
	v_pk_add_f32 v[118:119], v[118:119], v[130:131]
	v_pk_add_f32 v[120:121], v[120:121], v[134:135]
	v_mov_b32_e32 v131, v118
	v_mov_b32_e32 v130, v120
	v_mov_b32_e32 v118, v121
	v_pk_add_f32 v[118:119], v[130:131], v[118:119]
	s_mov_b32 s4, 0x3b800000
	v_pk_fma_f32 v[134:135], v[118:119], s[4:5], v[166:167] op_sel_hi:[1,0,0]
	v_mad_i64_i32 v[120:121], s[26:27], v196, s92, v[192:193]
	v_mul_f32_e32 v115, 0x4b800000, v135
	v_cmp_gt_f32_e32 vcc, s29, v135
	v_cvt_pk_bf16_f32 v240, v102, v103
	v_cvt_pk_bf16_f32 v241, v104, v105
	v_cndmask_b32_e32 v115, v135, v115, vcc
	v_rsq_f32_e32 v115, v115
	v_cvt_pk_bf16_f32 v242, v144, v145
	v_cvt_pk_bf16_f32 v243, v142, v143
	v_mul_f32_e32 v118, 0x45800000, v115
	v_cndmask_b32_e32 v115, v115, v118, vcc
	s_nop 1
	v_permlane16_swap_b32_e32 v240, v242
	v_permlane16_swap_b32_e32 v241, v243
	v_lshl_add_u64 v[214:215], v[120:121], 0, v[226:227]
	global_store_dwordx4 v[214:215], v[240:243], off
	v_mul_f32_e32 v118, 0x3e16c740, v115
	v_pk_mul_f32 v[132:133], v[90:91], v[118:119] op_sel_hi:[1,0]
	v_lshlrev_b64 v[90:91], 2, v[194:195]
	v_cmp_gt_f32_e64 s[4:5], s29, v134
	v_pk_mul_f32 v[96:97], v[96:97], v[118:119] op_sel_hi:[1,0]
	v_pk_mul_f32 v[94:95], v[94:95], v[118:119] op_sel_hi:[1,0]
	v_pk_mul_f32 v[130:131], v[92:93], v[118:119] op_sel_hi:[1,0]
	s_and_b64 vcc, exec, s[6:7]
	v_lshl_add_u64 v[92:93], v[162:163], 0, v[90:91]
	v_lshl_add_u64 v[102:103], v[164:165], 0, v[90:91]
	s_cbranch_vccnz .LBB0_532
	global_load_dwordx4 v[142:145], v[102:103], off
	global_load_dwordx4 v[146:149], v[92:93], off
	s_waitcnt vmcnt(0)
	v_pk_mul_f32 v[90:91], v[130:131], v[144:145]
	v_pk_mul_f32 v[104:105], v[132:133], v[142:143]
	v_pk_mul_f32 v[136:137], v[96:97], v[144:145]
	v_pk_mul_f32 v[142:143], v[94:95], v[142:143]
	s_waitcnt vmcnt(0)
	v_pk_fma_f32 v[96:97], v[96:97], v[148:149], v[90:91] neg_lo:[0,0,1] neg_hi:[0,0,1]
	v_pk_fma_f32 v[94:95], v[94:95], v[146:147], v[104:105] neg_lo:[0,0,1] neg_hi:[0,0,1]
	v_pk_fma_f32 v[130:131], v[130:131], v[148:149], v[136:137]
	v_pk_fma_f32 v[132:133], v[132:133], v[146:147], v[142:143]
.LBB0_532:
	v_mul_f32_e32 v90, 0x4b800000, v134
	v_cndmask_b32_e64 v90, v134, v90, s[4:5]
	v_rsq_f32_e32 v90, v90
	v_cvt_pk_bf16_f32 v244, v94, v95
	v_cvt_pk_bf16_f32 v245, v96, v97
	s_and_b64 vcc, exec, s[6:7]
	v_mul_f32_e32 v91, 0x45800000, v90
	v_cndmask_b32_e64 v90, v90, v91, s[4:5]
	v_mul_f32_e32 v90, 0x3e16c740, v90
	v_mad_i64_i32 v[104:105], s[4:5], v190, s92, v[192:193]
	v_cvt_pk_bf16_f32 v247, v130, v131
	v_pk_mul_f32 v[130:131], v[84:85], v[90:91] op_sel_hi:[1,0]
	v_lshlrev_b64 v[84:85], 2, v[188:189]
	v_cvt_pk_bf16_f32 v246, v132, v133
	v_pk_mul_f32 v[88:89], v[88:89], v[90:91] op_sel_hi:[1,0]
	v_pk_mul_f32 v[86:87], v[86:87], v[90:91] op_sel_hi:[1,0]
	v_pk_mul_f32 v[132:133], v[82:83], v[90:91] op_sel_hi:[1,0]
	v_lshl_add_u64 v[82:83], v[162:163], 0, v[84:85]
	v_lshl_add_u64 v[84:85], v[164:165], 0, v[84:85]
	s_nop 1
	v_permlane16_swap_b32_e32 v244, v246
	v_permlane16_swap_b32_e32 v245, v247
	v_lshl_add_u64 v[216:217], v[104:105], 0, v[226:227]
	global_store_dwordx4 v[216:217], v[244:247], off
	s_cbranch_vccnz .LBB0_534
	global_load_dwordx4 v[94:97], v[84:85], off
	global_load_dwordx4 v[134:137], v[82:83], off
	s_waitcnt vmcnt(0)
	v_pk_mul_f32 v[142:143], v[130:131], v[96:97]
	v_pk_mul_f32 v[144:145], v[132:133], v[94:95]
	v_pk_mul_f32 v[96:97], v[88:89], v[96:97]
	v_pk_mul_f32 v[94:95], v[86:87], v[94:95]
	s_waitcnt vmcnt(0)
	v_pk_fma_f32 v[88:89], v[88:89], v[136:137], v[142:143] neg_lo:[0,0,1] neg_hi:[0,0,1]
	v_pk_fma_f32 v[86:87], v[86:87], v[134:135], v[144:145] neg_lo:[0,0,1] neg_hi:[0,0,1]
	v_pk_fma_f32 v[130:131], v[130:131], v[136:137], v[96:97]
	v_pk_fma_f32 v[132:133], v[132:133], v[134:135], v[94:95]
.LBB0_534:
	s_waitcnt vmcnt(5)
	v_mov_b32_e32 v94, v107
	v_mov_b32_e32 v95, v108
	v_mov_b32_e32 v107, v109
	v_mov_b32_e32 v96, v111
	v_mov_b32_e32 v97, v112
	v_mov_b32_e32 v111, v113
	v_pk_add_f32 v[94:95], v[94:95], v[106:107]
	v_pk_add_f32 v[96:97], v[96:97], v[110:111]
	v_mov_b32_e32 v107, v94
	v_mov_b32_e32 v106, v96
	v_mov_b32_e32 v94, v97
	v_pk_add_f32 v[94:95], v[106:107], v[94:95]
	s_mov_b32 s4, 0x3b800000
	v_pk_fma_f32 v[110:111], v[94:95], s[4:5], v[166:167] op_sel_hi:[1,0,0]
	v_mad_i64_i32 v[96:97], s[26:27], v182, s92, v[192:193]
	v_mul_f32_e32 v91, 0x4b800000, v111
	v_cmp_gt_f32_e32 vcc, s29, v111
	v_cvt_pk_bf16_f32 v248, v86, v87
	v_cvt_pk_bf16_f32 v249, v88, v89
	v_cndmask_b32_e32 v91, v111, v91, vcc
	v_rsq_f32_e32 v91, v91
	v_cvt_pk_bf16_f32 v250, v132, v133
	v_cvt_pk_bf16_f32 v251, v130, v131
	v_mul_f32_e32 v94, 0x45800000, v91
	v_cndmask_b32_e32 v91, v91, v94, vcc
	s_nop 1
	v_permlane16_swap_b32_e32 v248, v250
	v_permlane16_swap_b32_e32 v249, v251
	v_lshl_add_u64 v[218:219], v[96:97], 0, v[226:227]
	global_store_dwordx4 v[218:219], v[248:251], off
	v_mul_f32_e32 v94, 0x3e16c740, v91
	v_pk_mul_f32 v[108:109], v[74:75], v[94:95] op_sel_hi:[1,0]
	v_lshlrev_b64 v[74:75], 2, v[180:181]
	v_cmp_gt_f32_e64 s[4:5], s29, v110
	v_pk_mul_f32 v[80:81], v[80:81], v[94:95] op_sel_hi:[1,0]
	v_pk_mul_f32 v[78:79], v[78:79], v[94:95] op_sel_hi:[1,0]
	v_pk_mul_f32 v[106:107], v[76:77], v[94:95] op_sel_hi:[1,0]
	s_and_b64 vcc, exec, s[6:7]
	v_lshl_add_u64 v[76:77], v[162:163], 0, v[74:75]
	v_lshl_add_u64 v[86:87], v[164:165], 0, v[74:75]
	s_cbranch_vccnz .LBB0_536
	global_load_dwordx4 v[130:133], v[86:87], off
	global_load_dwordx4 v[134:137], v[76:77], off
	s_waitcnt vmcnt(0)
	v_pk_mul_f32 v[74:75], v[106:107], v[132:133]
	v_pk_mul_f32 v[88:89], v[108:109], v[130:131]
	v_pk_mul_f32 v[112:113], v[80:81], v[132:133]
	v_pk_mul_f32 v[130:131], v[78:79], v[130:131]
	s_waitcnt vmcnt(0)
	v_pk_fma_f32 v[80:81], v[80:81], v[136:137], v[74:75] neg_lo:[0,0,1] neg_hi:[0,0,1]
	v_pk_fma_f32 v[78:79], v[78:79], v[134:135], v[88:89] neg_lo:[0,0,1] neg_hi:[0,0,1]
	v_pk_fma_f32 v[106:107], v[106:107], v[136:137], v[112:113]
	v_pk_fma_f32 v[108:109], v[108:109], v[134:135], v[130:131]
.LBB0_536:
	v_mul_f32_e32 v74, 0x4b800000, v110
	v_cndmask_b32_e64 v74, v110, v74, s[4:5]
	v_rsq_f32_e32 v74, v74
	v_cvt_pk_bf16_f32 v228, v78, v79
	v_cvt_pk_bf16_f32 v229, v80, v81
	s_and_b64 vcc, exec, s[6:7]
	v_mul_f32_e32 v75, 0x45800000, v74
	v_cndmask_b32_e64 v74, v74, v75, s[4:5]
	v_mul_f32_e32 v74, 0x3e16c740, v74
	v_mad_i64_i32 v[88:89], s[4:5], v178, s92, v[192:193]
	v_cvt_pk_bf16_f32 v230, v108, v109
	v_cvt_pk_bf16_f32 v231, v106, v107
	v_pk_mul_f32 v[106:107], v[66:67], v[74:75] op_sel_hi:[1,0]
	v_lshlrev_b64 v[66:67], 2, v[160:161]
	s_nop 1
	v_permlane16_swap_b32_e32 v228, v230
	v_permlane16_swap_b32_e32 v229, v231
	v_lshl_add_u64 v[214:215], v[88:89], 0, v[226:227]
	global_store_dwordx4 v[214:215], v[228:231], off
	v_pk_mul_f32 v[72:73], v[72:73], v[74:75] op_sel_hi:[1,0]
	v_pk_mul_f32 v[70:71], v[70:71], v[74:75] op_sel_hi:[1,0]
	v_pk_mul_f32 v[80:81], v[68:69], v[74:75] op_sel_hi:[1,0]
	v_lshl_add_u64 v[68:69], v[162:163], 0, v[66:67]
	v_lshl_add_u64 v[78:79], v[164:165], 0, v[66:67]
	s_cbranch_vccnz .LBB0_538
	global_load_dwordx4 v[108:111], v[78:79], off
	global_load_dwordx4 v[130:133], v[68:69], off
	s_waitcnt vmcnt(0)
	v_pk_mul_f32 v[66:67], v[80:81], v[110:111]
	v_pk_mul_f32 v[112:113], v[106:107], v[108:109]
	v_pk_mul_f32 v[110:111], v[72:73], v[110:111]
	v_pk_mul_f32 v[108:109], v[70:71], v[108:109]
	s_waitcnt vmcnt(0)
	v_pk_fma_f32 v[72:73], v[72:73], v[132:133], v[66:67] neg_lo:[0,0,1] neg_hi:[0,0,1]
	v_pk_fma_f32 v[70:71], v[70:71], v[130:131], v[112:113] neg_lo:[0,0,1] neg_hi:[0,0,1]
	v_pk_fma_f32 v[80:81], v[80:81], v[132:133], v[110:111]
	v_pk_fma_f32 v[106:107], v[106:107], v[130:131], v[108:109]
.LBB0_538:
	v_mad_i64_i32 v[66:67], s[4:5], v158, s92, v[192:193]
	s_or_b32 s4, s15, 4
	s_mul_hi_i32 s5, s4, 0x55555556
	v_cvt_pk_bf16_f32 v232, v70, v71
	v_cvt_pk_bf16_f32 v233, v72, v73
	s_lshr_b32 s6, s5, 31
	v_cvt_pk_bf16_f32 v234, v106, v107
	v_cvt_pk_bf16_f32 v235, v80, v81
	s_add_i32 s5, s5, s6
	s_nop 1
	v_permlane16_swap_b32_e32 v232, v234
	v_permlane16_swap_b32_e32 v233, v235
	v_lshl_add_u64 v[216:217], v[66:67], 0, v[226:227]
	global_store_dwordx4 v[216:217], v[232:235], off
	s_mul_i32 s5, s5, 3
	s_sub_i32 s4, s4, s5
	v_mov_b32_e32 v157, v156
	s_cmp_eq_u32 s4, 2
	v_mov_b32_e32 v70, v156
	v_mov_b32_e32 v71, v156
	s_cselect_b64 s[6:7], -1, 0
	s_cmp_lg_u32 s4, 2
	v_pk_mul_f32 v[64:65], v[64:65], v[70:71]
	v_pk_mul_f32 v[62:63], v[62:63], v[156:157]
	v_pk_mul_f32 v[60:61], v[60:61], v[70:71]
	v_pk_mul_f32 v[58:59], v[58:59], v[156:157]
	s_cbranch_scc1 .LBB0_540
	global_load_dwordx4 v[70:73], v[184:185], off
	global_load_dwordx4 v[106:109], v[150:151], off
	s_waitcnt vmcnt(0)
	v_pk_mul_f32 v[80:81], v[60:61], v[72:73]
	v_pk_mul_f32 v[110:111], v[58:59], v[70:71]
	v_pk_mul_f32 v[72:73], v[64:65], v[72:73]
	v_pk_mul_f32 v[70:71], v[62:63], v[70:71]
	s_waitcnt vmcnt(0)
	v_pk_fma_f32 v[64:65], v[64:65], v[108:109], v[80:81] neg_lo:[0,0,1] neg_hi:[0,0,1]
	v_pk_fma_f32 v[62:63], v[62:63], v[106:107], v[110:111] neg_lo:[0,0,1] neg_hi:[0,0,1]
	v_pk_fma_f32 v[60:61], v[60:61], v[108:109], v[72:73]
	v_pk_fma_f32 v[58:59], v[58:59], v[106:107], v[70:71]
.LBB0_540:
	s_nop 0
	v_cvt_pk_bf16_f32 v238, v58, v59
	v_cvt_pk_bf16_f32 v239, v60, v61
	v_mov_b32_e32 v58, v152
	v_mov_b32_e32 v59, v152
	v_mov_b32_e32 v153, v152
	v_pk_mul_f32 v[56:57], v[56:57], v[58:59]
	v_pk_mul_f32 v[52:53], v[52:53], v[58:59]
	v_cndmask_b32_e64 v58, 0, 1, s[6:7]
	v_cvt_pk_bf16_f32 v236, v62, v63
	v_cvt_pk_bf16_f32 v237, v64, v65
	v_pk_mul_f32 v[54:55], v[54:55], v[152:153]
	v_cmp_ne_u32_e64 s[4:5], 1, v58
	s_andn2_b64 vcc, exec, s[6:7]
	v_pk_mul_f32 v[50:51], v[50:51], v[152:153]
	s_nop 1
	v_permlane16_swap_b32_e32 v236, v238
	v_permlane16_swap_b32_e32 v237, v239
	v_lshl_add_u64 v[218:219], v[186:187], 0, v[226:227]
	global_store_dwordx4 v[218:219], v[236:239], off offset:256
	s_cbranch_vccnz .LBB0_542
	global_load_dwordx4 v[58:61], v[124:125], off
	global_load_dwordx4 v[62:65], v[122:123], off
	s_waitcnt vmcnt(0)
	v_pk_mul_f32 v[70:71], v[52:53], v[60:61]
	v_pk_mul_f32 v[72:73], v[50:51], v[58:59]
	v_pk_mul_f32 v[60:61], v[56:57], v[60:61]
	v_pk_mul_f32 v[58:59], v[54:55], v[58:59]
	s_waitcnt vmcnt(0)
	v_pk_fma_f32 v[56:57], v[56:57], v[64:65], v[70:71] neg_lo:[0,0,1] neg_hi:[0,0,1]
	v_pk_fma_f32 v[54:55], v[54:55], v[62:63], v[72:73] neg_lo:[0,0,1] neg_hi:[0,0,1]
	v_pk_fma_f32 v[52:53], v[52:53], v[64:65], v[60:61]
	v_pk_fma_f32 v[50:51], v[50:51], v[62:63], v[58:59]
.LBB0_542:
	v_cvt_pk_bf16_f32 v240, v54, v55
	v_cvt_pk_bf16_f32 v241, v56, v57
	v_cvt_pk_bf16_f32 v242, v50, v51
	v_cvt_pk_bf16_f32 v243, v52, v53
	s_nop 1
	v_permlane16_swap_b32_e32 v240, v242
	v_permlane16_swap_b32_e32 v241, v243
	v_lshl_add_u64 v[214:215], v[140:141], 0, v[226:227]
	global_store_dwordx4 v[214:215], v[240:243], off offset:256
	v_mov_b32_e32 v139, v138
	v_mov_b32_e32 v50, v138
	v_mov_b32_e32 v51, v138
	v_pk_mul_f32 v[48:49], v[48:49], v[50:51]
	v_pk_mul_f32 v[46:47], v[46:47], v[138:139]
	v_pk_mul_f32 v[44:45], v[44:45], v[50:51]
	s_and_b64 vcc, exec, s[4:5]
	v_pk_mul_f32 v[42:43], v[42:43], v[138:139]
	s_cbranch_vccnz .LBB0_544
	global_load_dwordx4 v[50:53], v[126:127], off
	global_load_dwordx4 v[54:57], v[116:117], off
	s_waitcnt vmcnt(0)
	v_pk_mul_f32 v[58:59], v[44:45], v[52:53]
	v_pk_mul_f32 v[60:61], v[42:43], v[50:51]
	v_pk_mul_f32 v[52:53], v[48:49], v[52:53]
	v_pk_mul_f32 v[50:51], v[46:47], v[50:51]
	s_waitcnt vmcnt(0)
	v_pk_fma_f32 v[48:49], v[48:49], v[56:57], v[58:59] neg_lo:[0,0,1] neg_hi:[0,0,1]
	v_pk_fma_f32 v[46:47], v[46:47], v[54:55], v[60:61] neg_lo:[0,0,1] neg_hi:[0,0,1]
	v_pk_fma_f32 v[44:45], v[44:45], v[56:57], v[52:53]
	v_pk_fma_f32 v[42:43], v[42:43], v[54:55], v[50:51]
.LBB0_544:
	s_nop 0
	v_cvt_pk_bf16_f32 v246, v42, v43
	v_cvt_pk_bf16_f32 v247, v44, v45
	v_mov_b32_e32 v115, v114
	v_mov_b32_e32 v42, v114
	v_mov_b32_e32 v43, v114
	v_cvt_pk_bf16_f32 v244, v46, v47
	v_cvt_pk_bf16_f32 v245, v48, v49
	v_pk_mul_f32 v[40:41], v[40:41], v[42:43]
	v_pk_mul_f32 v[38:39], v[38:39], v[114:115]
	v_pk_mul_f32 v[36:37], v[36:37], v[42:43]
	s_and_b64 vcc, exec, s[4:5]
	v_pk_mul_f32 v[34:35], v[34:35], v[114:115]
	s_nop 1
	v_permlane16_swap_b32_e32 v244, v246
	v_permlane16_swap_b32_e32 v245, v247
	v_lshl_add_u64 v[216:217], v[128:129], 0, v[226:227]
	global_store_dwordx4 v[216:217], v[244:247], off offset:256
	s_cbranch_vccnz .LBB0_546
	global_load_dwordx4 v[42:45], v[100:101], off
	global_load_dwordx4 v[46:49], v[98:99], off
	s_waitcnt vmcnt(0)
	v_pk_mul_f32 v[50:51], v[36:37], v[44:45]
	v_pk_mul_f32 v[52:53], v[34:35], v[42:43]
	v_pk_mul_f32 v[44:45], v[40:41], v[44:45]
	v_pk_mul_f32 v[42:43], v[38:39], v[42:43]
	s_waitcnt vmcnt(0)
	v_pk_fma_f32 v[40:41], v[40:41], v[48:49], v[50:51] neg_lo:[0,0,1] neg_hi:[0,0,1]
	v_pk_fma_f32 v[38:39], v[38:39], v[46:47], v[52:53] neg_lo:[0,0,1] neg_hi:[0,0,1]
	v_pk_fma_f32 v[36:37], v[36:37], v[48:49], v[44:45]
	v_pk_fma_f32 v[34:35], v[34:35], v[46:47], v[42:43]
.LBB0_546:
	v_cvt_pk_bf16_f32 v248, v38, v39
	v_cvt_pk_bf16_f32 v249, v40, v41
	v_cvt_pk_bf16_f32 v250, v34, v35
	v_cvt_pk_bf16_f32 v251, v36, v37
	s_nop 1
	v_permlane16_swap_b32_e32 v248, v250
	v_permlane16_swap_b32_e32 v249, v251
	v_lshl_add_u64 v[218:219], v[120:121], 0, v[226:227]
	global_store_dwordx4 v[218:219], v[248:251], off offset:256
	v_mov_b32_e32 v119, v118
	v_mov_b32_e32 v34, v118
	v_mov_b32_e32 v35, v118
	v_pk_mul_f32 v[32:33], v[32:33], v[34:35]
	v_pk_mul_f32 v[30:31], v[30:31], v[118:119]
	v_pk_mul_f32 v[28:29], v[28:29], v[34:35]
	s_and_b64 vcc, exec, s[4:5]
	v_pk_mul_f32 v[26:27], v[26:27], v[118:119]
	s_cbranch_vccnz .LBB0_548
	global_load_dwordx4 v[34:37], v[102:103], off
	global_load_dwordx4 v[38:41], v[92:93], off
	s_waitcnt vmcnt(0)
	v_pk_mul_f32 v[42:43], v[28:29], v[36:37]
	v_pk_mul_f32 v[44:45], v[26:27], v[34:35]
	v_pk_mul_f32 v[36:37], v[32:33], v[36:37]
	v_pk_mul_f32 v[34:35], v[30:31], v[34:35]
	s_waitcnt vmcnt(0)
	v_pk_fma_f32 v[32:33], v[32:33], v[40:41], v[42:43] neg_lo:[0,0,1] neg_hi:[0,0,1]
	v_pk_fma_f32 v[30:31], v[30:31], v[38:39], v[44:45] neg_lo:[0,0,1] neg_hi:[0,0,1]
	v_pk_fma_f32 v[28:29], v[28:29], v[40:41], v[36:37]
	v_pk_fma_f32 v[26:27], v[26:27], v[38:39], v[34:35]
.LBB0_548:
	s_nop 0
	v_cvt_pk_bf16_f32 v230, v26, v27
	v_cvt_pk_bf16_f32 v231, v28, v29
	v_mov_b32_e32 v91, v90
	v_mov_b32_e32 v26, v90
	v_mov_b32_e32 v27, v90
	v_cvt_pk_bf16_f32 v228, v30, v31
	v_cvt_pk_bf16_f32 v229, v32, v33
	v_pk_mul_f32 v[24:25], v[24:25], v[26:27]
	v_pk_mul_f32 v[22:23], v[22:23], v[90:91]
	v_pk_mul_f32 v[20:21], v[20:21], v[26:27]
	s_and_b64 vcc, exec, s[4:5]
	v_pk_mul_f32 v[18:19], v[18:19], v[90:91]
	s_nop 1
	v_permlane16_swap_b32_e32 v228, v230
	v_permlane16_swap_b32_e32 v229, v231
	v_lshl_add_u64 v[214:215], v[104:105], 0, v[226:227]
	global_store_dwordx4 v[214:215], v[228:231], off offset:256
	s_cbranch_vccnz .LBB0_550
	global_load_dwordx4 v[26:29], v[84:85], off
	global_load_dwordx4 v[30:33], v[82:83], off
	s_waitcnt vmcnt(0)
	v_pk_mul_f32 v[34:35], v[20:21], v[28:29]
	v_pk_mul_f32 v[36:37], v[18:19], v[26:27]
	v_pk_mul_f32 v[28:29], v[24:25], v[28:29]
	v_pk_mul_f32 v[26:27], v[22:23], v[26:27]
	s_waitcnt vmcnt(0)
	v_pk_fma_f32 v[24:25], v[24:25], v[32:33], v[34:35] neg_lo:[0,0,1] neg_hi:[0,0,1]
	v_pk_fma_f32 v[22:23], v[22:23], v[30:31], v[36:37] neg_lo:[0,0,1] neg_hi:[0,0,1]
	v_pk_fma_f32 v[20:21], v[20:21], v[32:33], v[28:29]
	v_pk_fma_f32 v[18:19], v[18:19], v[30:31], v[26:27]
.LBB0_550:
	v_cvt_pk_bf16_f32 v232, v22, v23
	v_cvt_pk_bf16_f32 v233, v24, v25
	v_cvt_pk_bf16_f32 v234, v18, v19
	v_cvt_pk_bf16_f32 v235, v20, v21
	s_nop 1
	v_permlane16_swap_b32_e32 v232, v234
	v_permlane16_swap_b32_e32 v233, v235
	v_lshl_add_u64 v[216:217], v[96:97], 0, v[226:227]
	global_store_dwordx4 v[216:217], v[232:235], off offset:256
	v_mov_b32_e32 v95, v94
	v_mov_b32_e32 v18, v94
	v_mov_b32_e32 v19, v94
	v_pk_mul_f32 v[16:17], v[16:17], v[18:19]
	v_pk_mul_f32 v[14:15], v[14:15], v[94:95]
	v_pk_mul_f32 v[10:11], v[10:11], v[18:19]
	s_and_b64 vcc, exec, s[4:5]
	v_pk_mul_f32 v[8:9], v[8:9], v[94:95]
	s_cbranch_vccnz .LBB0_552
	global_load_dwordx4 v[18:21], v[86:87], off
	global_load_dwordx4 v[22:25], v[76:77], off
	s_waitcnt vmcnt(0)
	v_pk_mul_f32 v[26:27], v[10:11], v[20:21]
	v_pk_mul_f32 v[28:29], v[8:9], v[18:19]
	v_pk_mul_f32 v[20:21], v[16:17], v[20:21]
	v_pk_mul_f32 v[18:19], v[14:15], v[18:19]
	s_waitcnt vmcnt(0)
	v_pk_fma_f32 v[16:17], v[16:17], v[24:25], v[26:27] neg_lo:[0,0,1] neg_hi:[0,0,1]
	v_pk_fma_f32 v[14:15], v[14:15], v[22:23], v[28:29] neg_lo:[0,0,1] neg_hi:[0,0,1]
	v_pk_fma_f32 v[10:11], v[10:11], v[24:25], v[20:21]
	v_pk_fma_f32 v[8:9], v[8:9], v[22:23], v[18:19]
.LBB0_552:
	s_nop 0
	v_cvt_pk_bf16_f32 v238, v8, v9
	v_cvt_pk_bf16_f32 v239, v10, v11
	v_mov_b32_e32 v75, v74
	v_mov_b32_e32 v8, v74
	v_mov_b32_e32 v9, v74
	v_cvt_pk_bf16_f32 v236, v14, v15
	v_cvt_pk_bf16_f32 v237, v16, v17
	v_pk_mul_f32 v[6:7], v[6:7], v[8:9]
	v_pk_mul_f32 v[4:5], v[4:5], v[74:75]
	v_pk_mul_f32 v[2:3], v[2:3], v[8:9]
	s_and_b64 vcc, exec, s[4:5]
	v_pk_mul_f32 v[0:1], v[0:1], v[74:75]
	s_nop 1
	v_permlane16_swap_b32_e32 v236, v238
	v_permlane16_swap_b32_e32 v237, v239
	v_lshl_add_u64 v[218:219], v[88:89], 0, v[226:227]
	global_store_dwordx4 v[218:219], v[236:239], off offset:256
	s_cbranch_vccnz .LBB0_554
	global_load_dwordx4 v[8:11], v[78:79], off
	global_load_dwordx4 v[14:17], v[68:69], off
	s_waitcnt vmcnt(0)
	v_pk_mul_f32 v[18:19], v[2:3], v[10:11]
	v_pk_mul_f32 v[20:21], v[0:1], v[8:9]
	v_pk_mul_f32 v[10:11], v[6:7], v[10:11]
	v_pk_mul_f32 v[8:9], v[4:5], v[8:9]
	s_waitcnt vmcnt(0)
	v_pk_fma_f32 v[6:7], v[6:7], v[16:17], v[18:19] neg_lo:[0,0,1] neg_hi:[0,0,1]
	v_pk_fma_f32 v[4:5], v[4:5], v[14:15], v[20:21] neg_lo:[0,0,1] neg_hi:[0,0,1]
	v_pk_fma_f32 v[2:3], v[2:3], v[16:17], v[10:11]
	v_pk_fma_f32 v[0:1], v[0:1], v[14:15], v[8:9]
.LBB0_554:
	v_cvt_pk_bf16_f32 v240, v4, v5
	v_cvt_pk_bf16_f32 v241, v6, v7
	v_cvt_pk_bf16_f32 v242, v0, v1
	v_cvt_pk_bf16_f32 v243, v2, v3
	s_nop 1
	v_permlane16_swap_b32_e32 v240, v242
	v_permlane16_swap_b32_e32 v241, v243
	v_lshl_add_u64 v[214:215], v[66:67], 0, v[226:227]
	global_store_dwordx4 v[214:215], v[240:243], off offset:256
	s_andn2_b64 vcc, exec, s[0:1]
	s_mov_b64 s[0:1], -1
	s_cbranch_vccnz .LBB0_517
	s_andn2_b64 vcc, exec, s[8:9]
	s_cbranch_vccnz .LBB0_516
	s_barrier
	s_branch .LBB0_516

.LBB0_572:
	v_mbcnt_lo_u32_b32 v176, -1, 0
	v_mbcnt_hi_u32_b32 v176, -1, v176
	v_and_b32_e32 v176, 16, v176
	v_lshrrev_b32_e32 v177, 1, v176
	v_add_u32_e32 v176, v176, v177
	v_mov_b32_e32 v177, 0
	s_lshl_b32 s6, s74, 8
	v_mov_b32_e32 v130, v252
	v_mov_b32_e32 v149, v221
	s_add_i32 s6, s6, s41
	s_brev_b32 s16, 60
	v_add_u32_e32 v144, s6, v130
	v_ashrrev_i32_e32 v145, 31, v144
	v_lshl_add_u64 v[130:131], v[144:145], 4, s[88:89]
	global_load_dwordx4 v[206:209], v[130:131], off
	global_load_dwordx4 v[210:213], v[130:131], off offset:256
	global_load_dwordx4 v[214:217], v[130:131], off offset:512
	global_load_dwordx4 v[222:225], v[130:131], off offset:768
	global_load_dwordx4 v[226:229], v[130:131], off offset:2048
	global_load_dwordx4 v[230:233], v[130:131], off offset:2304
	global_load_dwordx4 v[234:237], v[130:131], off offset:2560
	global_load_dwordx4 v[238:241], v[130:131], off offset:2816
	v_add_u32_e32 v146, 16, v144
	v_ashrrev_i32_e32 v147, 31, v146
	s_mov_b32 s6, 0x358637bd
	v_mov_b64_e32 v[150:151], s[6:7]
	v_add_u32_e32 v154, 32, v144
	v_ashrrev_i32_e32 v155, 31, v154
	v_add_u32_e32 v156, 48, v144
	v_ashrrev_i32_e32 v157, 31, v156
	v_add_u32_e32 v160, 0x90, v144
	v_ashrrev_i32_e32 v161, 31, v160
	s_waitcnt vmcnt(7)
	v_mov_b32_e32 v130, v206
	v_mov_b32_e32 v131, v207
	v_mov_b32_e32 v132, v208
	v_mov_b32_e32 v133, v209
	v_mov_b32_e32 v136, v131
	v_mov_b32_e32 v137, v132
	v_mov_b32_e32 v131, v133
	v_pk_add_f32 v[136:137], v[136:137], v[130:131]
	v_lshl_add_u64 v[130:131], v[146:147], 4, s[88:89]
	s_waitcnt vmcnt(6)
	v_mov_b32_e32 v130, v210
	v_mov_b32_e32 v131, v211
	v_mov_b32_e32 v132, v212
	v_mov_b32_e32 v133, v213
	v_mov_b32_e32 v138, v131
	v_mov_b32_e32 v139, v132
	v_mov_b32_e32 v131, v133
	v_pk_add_f32 v[130:131], v[138:139], v[130:131]
	v_mov_b32_e32 v133, v136
	v_mov_b32_e32 v132, v130
	v_mov_b32_e32 v136, v131
	v_pk_add_f32 v[130:131], v[132:133], v[136:137]
	s_nop 0
	v_pk_fma_f32 v[130:131], v[130:131], s[16:17], v[150:151] op_sel_hi:[1,0,0]
	s_nop 0
	v_mul_f32_e32 v132, 0x4b800000, v131
	v_cmp_gt_f32_e64 s[6:7], s29, v131
	v_cmp_gt_f32_e32 vcc, s29, v130
	s_nop 0
	v_cndmask_b32_e64 v131, v131, v132, s[6:7]
	v_rsq_f32_e32 v131, v131
	s_nop 0
	v_mul_f32_e32 v132, 0x45800000, v131
	v_cndmask_b32_e64 v138, v131, v132, s[6:7]
	v_mul_f32_e32 v131, 0x4b800000, v130
	v_cndmask_b32_e32 v130, v130, v131, vcc
	v_rsq_f32_e32 v130, v130
	v_pk_mul_f32 v[124:125], v[124:125], v[138:139] op_sel_hi:[1,0]
	v_pk_mul_f32 v[122:123], v[122:123], v[138:139] op_sel_hi:[1,0]
	v_pk_mul_f32 v[128:129], v[128:129], v[138:139] op_sel_hi:[1,0]
	v_mul_f32_e32 v131, 0x45800000, v130
	v_cndmask_b32_e32 v136, v130, v131, vcc
	v_lshl_add_u64 v[130:131], v[154:155], 4, s[88:89]
	v_cvt_pk_bf16_f32 v122, v122, v123
	v_cvt_pk_bf16_f32 v123, v124, v125
	v_pk_mul_f32 v[108:109], v[108:109], v[136:137] op_sel_hi:[1,0]
	v_pk_mul_f32 v[106:107], v[106:107], v[136:137] op_sel_hi:[1,0]
	v_pk_mul_f32 v[126:127], v[126:127], v[138:139] op_sel_hi:[1,0]
	v_cvt_pk_bf16_f32 v106, v106, v107
	v_cvt_pk_bf16_f32 v107, v108, v109
	v_pk_mul_f32 v[112:113], v[112:113], v[136:137] op_sel_hi:[1,0]
	v_pk_mul_f32 v[110:111], v[110:111], v[136:137] op_sel_hi:[1,0]
	v_pk_mul_f32 v[56:57], v[56:57], v[138:139] op_sel_hi:[1,0]
	v_pk_mul_f32 v[54:55], v[54:55], v[138:139] op_sel_hi:[1,0]
	v_cvt_pk_bf16_f32 v126, v126, v127
	v_cvt_pk_bf16_f32 v127, v128, v129
	v_cvt_pk_bf16_f32 v110, v110, v111
	v_cvt_pk_bf16_f32 v111, v112, v113
	v_cvt_pk_bf16_f32 v54, v54, v55
	v_cvt_pk_bf16_f32 v55, v56, v57
	v_pk_mul_f32 v[40:41], v[40:41], v[136:137] op_sel_hi:[1,0]
	v_pk_mul_f32 v[38:39], v[38:39], v[136:137] op_sel_hi:[1,0]
	v_pk_mul_f32 v[64:65], v[64:65], v[138:139] op_sel_hi:[1,0]
	v_cvt_pk_bf16_f32 v38, v38, v39
	v_cvt_pk_bf16_f32 v39, v40, v41
	v_pk_mul_f32 v[62:63], v[62:63], v[138:139] op_sel_hi:[1,0]
	v_pk_mul_f32 v[48:49], v[48:49], v[136:137] op_sel_hi:[1,0]
	v_pk_mul_f32 v[46:47], v[46:47], v[136:137] op_sel_hi:[1,0]
	v_cvt_pk_bf16_f32 v62, v62, v63
	v_cvt_pk_bf16_f32 v63, v64, v65
	v_cvt_pk_bf16_f32 v46, v46, v47
	v_cvt_pk_bf16_f32 v47, v48, v49
	s_waitcnt vmcnt(5)
	v_mov_b32_e32 v130, v214
	v_mov_b32_e32 v131, v215
	v_mov_b32_e32 v132, v216
	v_mov_b32_e32 v133, v217
	v_mov_b32_e32 v152, v131
	v_mov_b32_e32 v153, v132
	v_mov_b32_e32 v131, v133
	v_pk_add_f32 v[152:153], v[152:153], v[130:131]
	v_lshl_add_u64 v[130:131], v[156:157], 4, s[88:89]
	s_waitcnt vmcnt(4)
	v_mov_b32_e32 v130, v222
	v_mov_b32_e32 v131, v223
	v_mov_b32_e32 v132, v224
	v_mov_b32_e32 v133, v225
	v_mov_b32_e32 v158, v131
	v_mov_b32_e32 v159, v132
	v_mov_b32_e32 v131, v133
	v_pk_add_f32 v[130:131], v[158:159], v[130:131]
	v_mov_b32_e32 v133, v152
	v_mov_b32_e32 v132, v130
	v_mov_b32_e32 v152, v131
	v_pk_add_f32 v[130:131], v[132:133], v[152:153]
	v_add_u32_e32 v158, 0x80, v144
	v_pk_fma_f32 v[130:131], v[130:131], s[16:17], v[150:151] op_sel_hi:[1,0,0]
	v_ashrrev_i32_e32 v159, 31, v158
	v_mul_f32_e32 v132, 0x4b800000, v131
	v_cmp_gt_f32_e64 s[6:7], s29, v131
	v_cmp_gt_f32_e32 vcc, s29, v130
	s_nop 0
	v_cndmask_b32_e64 v131, v131, v132, s[6:7]
	v_rsq_f32_e32 v131, v131
	s_nop 0
	v_mul_f32_e32 v132, 0x45800000, v131
	v_cndmask_b32_e64 v142, v131, v132, s[6:7]
	v_mul_f32_e32 v131, 0x4b800000, v130
	v_cndmask_b32_e32 v130, v130, v131, vcc
	v_rsq_f32_e32 v130, v130
	v_pk_mul_f32 v[92:93], v[92:93], v[142:143] op_sel_hi:[1,0]
	v_pk_mul_f32 v[90:91], v[90:91], v[142:143] op_sel_hi:[1,0]
	v_pk_mul_f32 v[96:97], v[96:97], v[142:143] op_sel_hi:[1,0]
	v_mul_f32_e32 v131, 0x45800000, v130
	v_cndmask_b32_e32 v140, v130, v131, vcc
	v_lshl_add_u64 v[130:131], v[158:159], 4, s[88:89]
	v_cvt_pk_bf16_f32 v90, v90, v91
	v_cvt_pk_bf16_f32 v91, v92, v93
	v_pk_mul_f32 v[80:81], v[80:81], v[140:141] op_sel_hi:[1,0]
	v_pk_mul_f32 v[78:79], v[78:79], v[140:141] op_sel_hi:[1,0]
	v_pk_mul_f32 v[76:77], v[76:77], v[140:141] op_sel_hi:[1,0]
	v_pk_mul_f32 v[74:75], v[74:75], v[140:141] op_sel_hi:[1,0]
	v_cvt_pk_bf16_f32 v180, v78, v79
	v_cvt_pk_bf16_f32 v181, v80, v81
	v_cvt_pk_bf16_f32 v182, v74, v75
	v_cvt_pk_bf16_f32 v183, v76, v77
	v_pk_mul_f32 v[94:95], v[94:95], v[142:143] op_sel_hi:[1,0]
	v_pk_mul_f32 v[24:25], v[24:25], v[142:143] op_sel_hi:[1,0]
	v_cvt_pk_bf16_f32 v94, v94, v95
	v_cvt_pk_bf16_f32 v95, v96, v97
	v_pk_mul_f32 v[22:23], v[22:23], v[142:143] op_sel_hi:[1,0]
	v_pk_mul_f32 v[16:17], v[16:17], v[140:141] op_sel_hi:[1,0]
	v_cvt_pk_bf16_f32 v22, v22, v23
	v_cvt_pk_bf16_f32 v23, v24, v25
	v_pk_mul_f32 v[14:15], v[14:15], v[140:141] op_sel_hi:[1,0]
	v_pk_mul_f32 v[6:7], v[6:7], v[140:141] op_sel_hi:[1,0]
	v_cvt_pk_bf16_f32 v196, v14, v15
	v_cvt_pk_bf16_f32 v197, v16, v17
	v_pk_mul_f32 v[4:5], v[4:5], v[140:141] op_sel_hi:[1,0]
	v_pk_mul_f32 v[32:33], v[32:33], v[142:143] op_sel_hi:[1,0]
	v_cvt_pk_bf16_f32 v198, v4, v5
	v_cvt_pk_bf16_f32 v199, v6, v7
	v_pk_mul_f32 v[30:31], v[30:31], v[142:143] op_sel_hi:[1,0]
	s_waitcnt vmcnt(3)
	v_mov_b32_e32 v130, v226
	v_mov_b32_e32 v131, v227
	v_mov_b32_e32 v132, v228
	v_mov_b32_e32 v133, v229
	v_mov_b32_e32 v152, v131
	v_mov_b32_e32 v153, v132
	v_mov_b32_e32 v131, v133
	v_pk_add_f32 v[152:153], v[152:153], v[130:131]
	v_lshl_add_u64 v[130:131], v[160:161], 4, s[88:89]
	v_cvt_pk_bf16_f32 v30, v30, v31
	v_cvt_pk_bf16_f32 v31, v32, v33
	s_waitcnt vmcnt(2)
	v_mov_b32_e32 v130, v230
	v_mov_b32_e32 v131, v231
	v_mov_b32_e32 v132, v232
	v_mov_b32_e32 v133, v233
	v_mov_b32_e32 v162, v131
	v_mov_b32_e32 v163, v132
	v_mov_b32_e32 v131, v133
	v_pk_add_f32 v[130:131], v[162:163], v[130:131]
	v_mov_b32_e32 v133, v152
	v_mov_b32_e32 v132, v130
	v_mov_b32_e32 v152, v131
	v_pk_add_f32 v[130:131], v[132:133], v[152:153]
	v_add_u32_e32 v162, 0xa0, v144
	v_pk_fma_f32 v[130:131], v[130:131], s[16:17], v[150:151] op_sel_hi:[1,0,0]
	v_ashrrev_i32_e32 v163, 31, v162
	v_mul_f32_e32 v132, 0x4b800000, v131
	v_cmp_gt_f32_e64 s[6:7], s29, v131
	v_cmp_gt_f32_e32 vcc, s29, v130
	s_nop 0
	v_cndmask_b32_e64 v131, v131, v132, s[6:7]
	v_rsq_f32_e32 v131, v131
	s_nop 0
	v_mul_f32_e32 v132, 0x45800000, v131
	v_cndmask_b32_e64 v152, v131, v132, s[6:7]
	v_mul_f32_e32 v131, 0x4b800000, v130
	v_cndmask_b32_e32 v130, v130, v131, vcc
	v_rsq_f32_e32 v130, v130
	v_pk_mul_f32 v[80:81], v[118:119], v[152:153] op_sel_hi:[1,0]
	v_pk_mul_f32 v[6:7], v[60:61], v[152:153] op_sel_hi:[1,0]
	v_cvt_pk_bf16_f32 v184, v80, v81
	v_mul_f32_e32 v131, 0x45800000, v130
	v_cndmask_b32_e32 v148, v130, v131, vcc
	v_lshl_add_u64 v[130:131], v[162:163], 4, s[88:89]
	s_waitcnt vmcnt(1)
	v_mov_b32_e32 v130, v234
	v_mov_b32_e32 v131, v235
	v_mov_b32_e32 v132, v236
	v_mov_b32_e32 v133, v237
	v_mov_b32_e32 v164, v131
	v_mov_b32_e32 v165, v132
	v_mov_b32_e32 v131, v133
	v_pk_add_f32 v[178:179], v[164:165], v[130:131]
	v_add_u32_e32 v164, 0xb0, v144
	v_ashrrev_i32_e32 v165, 31, v164
	v_lshl_add_u64 v[130:131], v[164:165], 4, s[88:89]
	v_lshlrev_b64 v[144:145], 10, v[144:145]
	s_waitcnt vmcnt(0)
	v_mov_b32_e32 v130, v238
	v_mov_b32_e32 v131, v239
	v_mov_b32_e32 v132, v240
	v_mov_b32_e32 v133, v241
	v_mov_b32_e32 v168, v131
	v_mov_b32_e32 v169, v132
	v_mov_b32_e32 v131, v133
	v_pk_add_f32 v[130:131], v[168:169], v[130:131]
	v_mov_b32_e32 v133, v178
	v_mov_b32_e32 v132, v130
	v_mov_b32_e32 v178, v131
	v_pk_add_f32 v[130:131], v[132:133], v[178:179]
	s_nop 0
	v_pk_fma_f32 v[132:133], v[130:131], s[16:17], v[150:151] op_sel_hi:[1,0,0]
	s_nop 0
	v_mul_f32_e32 v130, 0x4b800000, v133
	v_cmp_gt_f32_e64 s[6:7], s29, v133
	v_cmp_gt_f32_e32 vcc, s29, v132
	s_nop 0
	v_cndmask_b32_e64 v130, v133, v130, s[6:7]
	v_rsq_f32_e32 v130, v130
	s_nop 0
	v_mul_f32_e32 v131, 0x45800000, v130
	v_cndmask_b32_e64 v130, v130, v131, s[6:7]
	s_lshl_b32 s6, s67, 7
	s_or_b32 s6, s6, s66
	v_lshl_add_u32 v150, v149, 2, s6
	v_ashrrev_i32_e32 v151, 31, v150
	v_lshl_add_u64 v[168:169], v[150:151], 1, s[12:13]
	v_lshl_add_u64 v[170:171], v[168:169], 0, v[144:145]
	global_store_dwordx2 v[170:171], v[122:123], off offset:32
	v_lshlrev_b64 v[122:123], 10, v[146:147]
	v_lshl_add_u64 v[124:125], v[168:169], 0, v[122:123]
	global_store_dwordx2 v[124:125], v[106:107], off offset:32
	v_lshlrev_b64 v[106:107], 10, v[154:155]
	v_lshl_add_u64 v[108:109], v[168:169], 0, v[106:107]
	global_store_dwordx2 v[108:109], v[90:91], off offset:32
	v_lshlrev_b64 v[90:91], 10, v[156:157]
	v_lshl_add_u64 v[92:93], v[168:169], 0, v[90:91]
	s_nop 1
	v_permlane16_swap_b32_e32 v180, v182
	v_permlane16_swap_b32_e32 v181, v183
	v_lshl_add_u64 v[204:205], v[92:93], 0, v[176:177]
	global_store_dwordx4 v[204:205], v[180:183], off
	v_lshlrev_b64 v[74:75], 10, v[158:159]
	v_pk_mul_f32 v[78:79], v[120:121], v[152:153] op_sel_hi:[1,0]
	v_lshl_add_u64 v[76:77], v[168:169], 0, v[74:75]
	v_cvt_pk_bf16_f32 v185, v78, v79
	v_mul_f32_e32 v131, 0x4b800000, v132
	v_pk_mul_f32 v[78:79], v[116:117], v[152:153] op_sel_hi:[1,0]
	v_pk_mul_f32 v[80:81], v[114:115], v[152:153] op_sel_hi:[1,0]
	v_cndmask_b32_e32 v131, v132, v131, vcc
	v_cvt_pk_bf16_f32 v186, v80, v81
	v_cvt_pk_bf16_f32 v187, v78, v79
	v_rsq_f32_e32 v131, v131
	s_nop 1
	v_permlane16_swap_b32_e32 v184, v186
	v_permlane16_swap_b32_e32 v185, v187
	v_lshl_add_u64 v[218:219], v[76:77], 0, v[176:177]
	global_store_dwordx4 v[218:219], v[184:187], off
	v_lshlrev_b64 v[76:77], 10, v[160:161]
	v_pk_mul_f32 v[80:81], v[104:105], v[148:149] op_sel_hi:[1,0]
	v_pk_mul_f32 v[92:93], v[102:103], v[148:149] op_sel_hi:[1,0]
	v_lshl_add_u64 v[78:79], v[168:169], 0, v[76:77]
	v_cvt_pk_bf16_f32 v188, v92, v93
	v_cvt_pk_bf16_f32 v189, v80, v81
	v_pk_mul_f32 v[80:81], v[100:101], v[148:149] op_sel_hi:[1,0]
	v_pk_mul_f32 v[92:93], v[98:99], v[148:149] op_sel_hi:[1,0]
	v_mul_f32_e32 v132, 0x45800000, v131
	v_cvt_pk_bf16_f32 v190, v92, v93
	v_cvt_pk_bf16_f32 v191, v80, v81
	s_nop 1
	v_permlane16_swap_b32_e32 v188, v190
	v_permlane16_swap_b32_e32 v189, v191
	v_lshl_add_u64 v[242:243], v[78:79], 0, v[176:177]
	global_store_dwordx4 v[242:243], v[188:191], off
	v_lshlrev_b64 v[78:79], 10, v[162:163]
	v_pk_mul_f32 v[88:89], v[88:89], v[130:131] op_sel_hi:[1,0]
	v_pk_mul_f32 v[86:87], v[86:87], v[130:131] op_sel_hi:[1,0]
	v_pk_mul_f32 v[84:85], v[84:85], v[130:131] op_sel_hi:[1,0]
	v_pk_mul_f32 v[82:83], v[82:83], v[130:131] op_sel_hi:[1,0]
	v_cndmask_b32_e32 v132, v131, v132, vcc
	v_lshl_add_u64 v[80:81], v[168:169], 0, v[78:79]
	v_cvt_pk_bf16_f32 v192, v86, v87
	v_cvt_pk_bf16_f32 v193, v88, v89
	v_cvt_pk_bf16_f32 v194, v82, v83
	v_cvt_pk_bf16_f32 v195, v84, v85
	s_nop 1
	v_permlane16_swap_b32_e32 v192, v194
	v_permlane16_swap_b32_e32 v193, v195
	v_lshl_add_u64 v[172:173], v[80:81], 0, v[176:177]
	global_store_dwordx4 v[172:173], v[192:195], off
	v_lshlrev_b64 v[80:81], 10, v[164:165]
	v_pk_mul_f32 v[68:69], v[68:69], v[132:133] op_sel_hi:[1,0]
	v_pk_mul_f32 v[66:67], v[66:67], v[132:133] op_sel_hi:[1,0]
	v_lshl_add_u64 v[82:83], v[168:169], 0, v[80:81]
	v_cvt_pk_bf16_f32 v66, v66, v67
	v_cvt_pk_bf16_f32 v67, v68, v69
	global_store_dwordx2 v[82:83], v[66:67], off offset:32
	v_add_u32_e32 v66, 64, v150
	v_ashrrev_i32_e32 v67, 31, v66
	v_pk_mul_f32 v[72:73], v[72:73], v[132:133] op_sel_hi:[1,0]
	v_pk_mul_f32 v[70:71], v[70:71], v[132:133] op_sel_hi:[1,0]
	v_lshl_add_u64 v[66:67], v[66:67], 1, s[12:13]
	v_cvt_pk_bf16_f32 v70, v70, v71
	v_cvt_pk_bf16_f32 v71, v72, v73
	v_lshl_add_u64 v[68:69], v[66:67], 0, v[144:145]
	global_store_dwordx2 v[170:171], v[126:127], off
	global_store_dwordx2 v[124:125], v[110:111], off
	global_store_dwordx2 v[108:109], v[94:95], off
	global_store_dwordx2 v[82:83], v[70:71], off
	global_store_dwordx2 v[68:69], v[54:55], off offset:32
	v_lshl_add_u64 v[54:55], v[66:67], 0, v[122:123]
	global_store_dwordx2 v[54:55], v[38:39], off offset:32
	v_lshl_add_u64 v[38:39], v[66:67], 0, v[106:107]
	global_store_dwordx2 v[38:39], v[22:23], off offset:32
	v_lshl_add_u64 v[22:23], v[66:67], 0, v[90:91]
	v_pk_mul_f32 v[14:15], v[58:59], v[152:153] op_sel_hi:[1,0]
	s_nop 1
	v_permlane16_swap_b32_e32 v196, v198
	v_permlane16_swap_b32_e32 v197, v199
	v_lshl_add_u64 v[174:175], v[22:23], 0, v[176:177]
	global_store_dwordx4 v[174:175], v[196:199], off
	v_lshl_add_u64 v[4:5], v[66:67], 0, v[74:75]
	v_cvt_pk_bf16_f32 v200, v14, v15
	v_cvt_pk_bf16_f32 v201, v6, v7
	v_pk_mul_f32 v[6:7], v[52:53], v[152:153] op_sel_hi:[1,0]
	v_pk_mul_f32 v[14:15], v[50:51], v[152:153] op_sel_hi:[1,0]
	v_pk_mul_f32 v[8:9], v[8:9], v[132:133] op_sel_hi:[1,0]
	v_cvt_pk_bf16_f32 v202, v14, v15
	v_cvt_pk_bf16_f32 v203, v6, v7
	s_nop 1
	v_permlane16_swap_b32_e32 v200, v202
	v_permlane16_swap_b32_e32 v201, v203
	v_lshl_add_u64 v[204:205], v[4:5], 0, v[176:177]
	global_store_dwordx4 v[204:205], v[200:203], off
	v_pk_mul_f32 v[6:7], v[44:45], v[148:149] op_sel_hi:[1,0]
	v_pk_mul_f32 v[14:15], v[42:43], v[148:149] op_sel_hi:[1,0]
	v_lshl_add_u64 v[4:5], v[66:67], 0, v[76:77]
	v_cvt_pk_bf16_f32 v244, v14, v15
	v_cvt_pk_bf16_f32 v245, v6, v7
	v_pk_mul_f32 v[6:7], v[36:37], v[148:149] op_sel_hi:[1,0]
	v_pk_mul_f32 v[14:15], v[34:35], v[148:149] op_sel_hi:[1,0]
	v_pk_mul_f32 v[2:3], v[2:3], v[132:133] op_sel_hi:[1,0]
	v_cvt_pk_bf16_f32 v246, v14, v15
	v_cvt_pk_bf16_f32 v247, v6, v7
	s_nop 1
	v_permlane16_swap_b32_e32 v244, v246
	v_permlane16_swap_b32_e32 v245, v247
	v_lshl_add_u64 v[218:219], v[4:5], 0, v[176:177]
	global_store_dwordx4 v[218:219], v[244:247], off
	v_pk_mul_f32 v[6:7], v[28:29], v[130:131] op_sel_hi:[1,0]
	v_pk_mul_f32 v[14:15], v[26:27], v[130:131] op_sel_hi:[1,0]
	v_lshl_add_u64 v[4:5], v[66:67], 0, v[78:79]
	v_cvt_pk_bf16_f32 v248, v14, v15
	v_cvt_pk_bf16_f32 v249, v6, v7
	v_pk_mul_f32 v[6:7], v[20:21], v[130:131] op_sel_hi:[1,0]
	v_pk_mul_f32 v[14:15], v[18:19], v[130:131] op_sel_hi:[1,0]
	v_pk_mul_f32 v[0:1], v[0:1], v[132:133] op_sel_hi:[1,0]
	v_cvt_pk_bf16_f32 v250, v14, v15
	v_cvt_pk_bf16_f32 v251, v6, v7
	v_pk_mul_f32 v[6:7], v[10:11], v[132:133] op_sel_hi:[1,0]
	s_nop 1
	v_permlane16_swap_b32_e32 v248, v250
	v_permlane16_swap_b32_e32 v249, v251
	v_lshl_add_u64 v[242:243], v[4:5], 0, v[176:177]
	global_store_dwordx4 v[242:243], v[248:251], off
	v_lshl_add_u64 v[4:5], v[66:67], 0, v[80:81]
	v_cvt_pk_bf16_f32 v180, v8, v9
	v_cvt_pk_bf16_f32 v181, v6, v7
	v_cvt_pk_bf16_f32 v182, v0, v1
	v_cvt_pk_bf16_f32 v183, v2, v3
	s_mov_b64 s[6:7], -1
	s_andn2_b64 vcc, exec, s[4:5]
	global_store_dwordx2 v[68:69], v[62:63], off
	global_store_dwordx2 v[54:55], v[46:47], off
	global_store_dwordx2 v[38:39], v[30:31], off
	s_nop 1
	v_permlane16_swap_b32_e32 v180, v182
	v_permlane16_swap_b32_e32 v181, v183
	v_lshl_add_u64 v[172:173], v[4:5], 0, v[176:177]
	global_store_dwordx4 v[172:173], v[180:183], off
	s_cbranch_vccnz .LBB0_563
	s_andn2_b64 vcc, exec, s[8:9]
	s_cbranch_vccnz .LBB0_562
	s_barrier
	s_branch .LBB0_562
